# NA attention: Q fragment loads also use whole-row lane mapping with per-wave LDS re-fragmenting
# baseline (speedup 1.0000x reference)
; __device__ __forceinline__ void na_item(const bf16_t* __restrict__ PMIX, const bf16_t* __restrict__ GP, bf16_t* __restrict__ O, const float* __restrict__ bias, int item, int lane, LAS unsigned char* wl) {
;     ...
;     const int c0 = min(max(j - 8, 0), 48), r0 = min(max(gi - 4, 0), 56);
;     const bf16_t* qp = PMIX + (size_t)qrow * NMIXP + O_NAQ + h * 64 + hi * 8;
;     bf16x8 qf[4];
; #pragma unroll
;     for (int ks = 0; ks < 4; ++ks) qf[ks] = *reinterpret_cast<const bf16x8*>(qp + ks * 16);
.LBB0_601:
	s_and_b32 s6, s5, 15
	v_or_b32_e32 v187, s8, v164
	v_mov_b64_e32 v[0:1], s[74:75]
	v_sub_u32_e32 v2, v187, v164
	v_add_u32_e32 v2, v2, v167
	v_mad_i64_i32 v[0:1], s[2:3], v2, s71, v[0:1]
	s_lshl_b32 s72, s6, 7
	v_lshl_add_u64 v[0:1], v[0:1], 0, s[72:73]
	v_mov_b32_e32 v161, v195
	v_lshl_add_u64 v[0:1], v[0:1], 0, v[194:195]
	global_load_dwordx4 v[48:51], v[0:1], off offset:1664
	v_lshl_add_u64 v[52:53], v[0:1], 0, s[98:99]
	v_lshl_add_u64 v[56:57], v[52:53], 0, s[98:99]
	v_lshl_add_u64 v[60:61], v[56:57], 0, s[98:99]
	global_load_dwordx4 v[52:55], v[52:53], off offset:1664
	global_load_dwordx4 v[56:59], v[56:57], off offset:1664
	global_load_dwordx4 v[60:63], v[60:61], off offset:1664
	v_sub_u32_e64 v2, s7, 4 clamp
	s_mov_b64 s[2:3], -1
	v_readfirstlane_b32 s5, v2
	s_and_b64 vcc, exec, s[0:1]
	s_cbranch_vccz .LBB0_603
	s_lshl_b32 s2, s4, 8
	s_add_i32 s8, s2, 0x4000
	s_mov_b64 s[2:3], 0

; #define LAS __attribute__((address_space(3)))
; __device__ __forceinline__ void na_item(const bf16_t* __restrict__ PMIX, const bf16_t* __restrict__ GP, bf16_t* __restrict__ O, const float* __restrict__ bias, int item, int lane, LAS unsigned char* wl) {
;     ...
;     bf16x8 qf[4];
; #pragma unroll
;     for (int ks = 0; ks < 4; ++ks) qf[ks] = *reinterpret_cast<const bf16x8*>(qp + ks * 16);
;     f32x16 oT0 = {}, oT1 = {}; float m = -1e30f, l = 0.f;
;     const int ntiles = lat ? 24 : 8;
;     const float* bh = bias + h * (15 * 31);
;     LAS float* lbias = (LAS float*)(wl + 4608);
;     if (lat) {
; #pragma unroll
;         for (int i = 0; i < 4; ++i) { const int e = lane * 4 + i, krr = e >> 5, dc = e & 31; lbias[e] = bh[(r0 + krr - gi + 7) * 31 + min(dc, 30)] * LOG2E; }
;         asm volatile("s_waitcnt vmcnt(0) lgkmcnt(0)" ::: "memory"); __builtin_amdgcn_wave_barrier();
;     }
.LBB0_609:
	v_or_b32_e32 v0, s33, v164
	v_sub_u32_e64 v0, v0, 8 clamp
	v_min_u32_e32 v32, 48, v0
	v_add_u32_e32 v2, s1, v167
	v_mov_b64_e32 v[0:1], s[74:75]
	v_mad_i64_i32 v[2:3], s[2:3], v2, s71, v[0:1]
	v_lshl_add_u64 v[2:3], v[2:3], 0, s[72:73]
	v_mov_b32_e32 v161, v195
	v_lshl_add_u64 v[2:3], v[2:3], 0, v[194:195]
	global_load_dwordx4 v[96:99], v[2:3], off offset:3712
	v_lshl_add_u64 v[100:101], v[2:3], 0, s[98:99]
	v_lshl_add_u64 v[104:105], v[100:101], 0, s[98:99]
	v_lshl_add_u64 v[108:109], v[104:105], 0, s[98:99]
	global_load_dwordx4 v[100:103], v[100:101], off offset:3712
	global_load_dwordx4 v[104:107], v[104:105], off offset:3712
	global_load_dwordx4 v[108:111], v[108:109], off offset:3712
	v_add_u32_e32 v2, s1, v167
	v_mad_i64_i32 v[0:1], s[2:3], v2, s71, v[0:1]
	v_lshl_add_u64 v[0:1], v[0:1], 0, s[72:73]
	v_lshl_add_u64 v[0:1], v[0:1], 0, v[194:195]
	s_mov_b64 s[2:3], 0x1680
	v_lshl_add_u64 v[2:3], v[0:1], 0, s[2:3]
	v_add_co_u32_e32 v0, vcc, s96, v0
	v_cmp_lt_u32_e64 s[2:3], v168, v32
	s_nop 0
	v_addc_co_u32_e32 v1, vcc, 0, v1, vcc
	global_load_dwordx4 v[112:115], v[0:1], off offset:1664
	v_lshl_add_u64 v[124:125], v[2:3], 0, s[98:99]
	v_lshl_add_u64 v[120:121], v[124:125], 0, s[98:99]
	v_lshl_add_u64 v[116:117], v[120:121], 0, s[98:99]
	global_load_dwordx4 v[116:119], v[116:117], off
	global_load_dwordx4 v[120:123], v[120:121], off
	global_load_dwordx4 v[124:127], v[124:125], off
	s_waitcnt vmcnt(16)
	ds_write_b128 v184, v[48:51] offset:46080
	ds_write_b128 v184, v[52:55] offset:47232
	ds_write_b128 v184, v[56:59] offset:48384
	ds_write_b128 v184, v[60:63] offset:49536
	s_waitcnt lgkmcnt(0)
	ds_read_b128 v[48:51], v185 offset:46080
	ds_read_b128 v[52:55], v185 offset:46112
	ds_read_b128 v[56:59], v185 offset:46144
	ds_read_b128 v[60:63], v185 offset:46176
	s_waitcnt lgkmcnt(0)
	v_or_b32_e32 v0, 1, v168
	v_cmp_lt_u32_e64 s[6:7], v0, v32
	v_or_b32_e32 v0, 3, v168
	v_or_b32_e32 v1, 2, v168
	v_cmp_lt_u32_e64 s[10:11], v0, v32
	v_or_b32_e32 v0, 9, v168
	v_cmp_lt_u32_e64 s[4:5], v1, v32
	v_or_b32_e32 v1, 10, v168
	v_cmp_lt_u32_e64 s[14:15], v0, v32
	v_or_b32_e32 v0, 11, v168
	v_cmp_lt_u32_e64 s[12:13], v1, v32
	v_cmp_lt_u32_e64 s[16:17], v0, v32
	v_add_u32_e32 v0, s33, v164
	v_or_b32_e32 v1, 0x4a, v168
	v_sub_u32_e32 v1, v1, v0
	v_min_u32_e32 v1, 30, v1
	v_lshlrev_b32_e32 v161, 2, v1
	v_or_b32_e32 v1, 0x49, v168
	v_sub_u32_e32 v1, v1, v0
	v_min_u32_e32 v1, 30, v1
	v_lshlrev_b32_e32 v188, 2, v1
	v_sub_u32_e32 v1, v178, v0
	v_min_u32_e32 v1, 30, v1
	v_lshlrev_b32_e32 v189, 2, v1
	v_sub_u32_e32 v1, v179, v0
	v_min_u32_e32 v1, 30, v1
	v_lshlrev_b32_e32 v190, 2, v1
	v_sub_u32_e32 v1, v180, v0
	v_min_u32_e32 v1, 30, v1
	v_lshlrev_b32_e32 v191, 2, v1
	v_sub_u32_e32 v1, v181, v0
	v_min_u32_e32 v1, 30, v1
	v_lshlrev_b32_e32 v192, 2, v1
	v_sub_u32_e32 v1, v182, v0
	v_min_u32_e32 v1, 30, v1
	v_lshlrev_b32_e32 v193, 2, v1
	v_sub_u32_e32 v1, v183, v0
	v_min_u32_e32 v1, 30, v1
	v_sub_u32_e32 v0, v168, v0
	v_lshlrev_b32_e32 v198, 2, v1
	v_max_i32_e32 v1, 0xffffffc6, v0
	v_add_u32_e32 v1, 58, v1
	v_min_u32_e32 v1, 30, v1
	v_lshlrev_b32_e32 v199, 2, v1
	v_max_i32_e32 v1, 0xffffffc7, v0
	v_add_u32_e32 v1, 57, v1
	v_min_u32_e32 v1, 30, v1
	v_lshlrev_b32_e32 v200, 2, v1
	v_max_i32_e32 v1, 0xffffffc8, v0
	v_add_u32_e32 v1, 56, v1
	v_min_u32_e32 v1, 30, v1
	v_lshlrev_b32_e32 v201, 2, v1
	v_max_i32_e32 v1, 0xffffffc9, v0
	v_add_u32_e32 v1, 55, v1
	v_min_u32_e32 v1, 30, v1
	v_lshlrev_b32_e32 v202, 2, v1
	v_max_i32_e32 v1, 0xffffffce, v0
	v_add_u32_e32 v1, 50, v1
	v_min_u32_e32 v1, 30, v1
	v_lshlrev_b32_e32 v203, 2, v1
	v_max_i32_e32 v1, 0xffffffcf, v0
	v_add_u32_e32 v1, 49, v1
	v_min_u32_e32 v1, 30, v1
	v_lshlrev_b32_e32 v204, 2, v1
	v_max_i32_e32 v1, 0xffffffd0, v0
	v_add_u32_e32 v1, 48, v1
	v_min_u32_e32 v1, 30, v1
	v_lshlrev_b32_e32 v205, 2, v1
	v_max_i32_e32 v1, 0xffffffd1, v0
	v_add_u32_e32 v1, 47, v1
	v_min_u32_e32 v1, 30, v1
	v_lshlrev_b32_e32 v206, 2, v1
	v_max_i32_e32 v1, 0xffffffd6, v0
	v_add_u32_e32 v1, 42, v1
	v_min_u32_e32 v1, 30, v1
	v_lshlrev_b32_e32 v207, 2, v1
	v_max_i32_e32 v1, 0xffffffd7, v0
	v_add_u32_e32 v1, 41, v1
	v_min_u32_e32 v1, 30, v1
	v_lshlrev_b32_e32 v208, 2, v1
	v_max_i32_e32 v1, 0xffffffd8, v0
	v_add_u32_e32 v1, 40, v1
	v_min_u32_e32 v1, 30, v1
	v_lshlrev_b32_e32 v209, 2, v1
	v_max_i32_e32 v1, 0xffffffd9, v0
	v_add_u32_e32 v1, 39, v1
	v_min_u32_e32 v1, 30, v1
	v_lshlrev_b32_e32 v210, 2, v1
	v_max_i32_e32 v1, 0xffffffde, v0
	v_add_u32_e32 v1, 34, v1
	v_add_u32_e32 v2, 16, v32
	v_cmp_ge_u32_e32 vcc, v170, v32
	v_min_u32_e32 v1, 30, v1
	s_add_i32 s86, s0, 0x4000
	s_and_b64 s[18:19], vcc, s[2:3]
	v_cmp_ge_u32_e32 vcc, v171, v32
	v_cmp_lt_u32_e64 s[0:1], v171, v2
	v_lshlrev_b32_e32 v211, 2, v1
	v_max_i32_e32 v1, 0xffffffdf, v0
	s_and_b64 s[20:21], vcc, s[0:1]
	v_cmp_ge_u32_e32 vcc, v172, v32
	v_cmp_lt_u32_e64 s[0:1], v172, v2
	v_add_u32_e32 v1, 33, v1
	s_and_b64 s[22:23], vcc, s[0:1]
	v_cmp_ge_u32_e32 vcc, v173, v32
	v_cmp_lt_u32_e64 s[0:1], v173, v2
	v_min_u32_e32 v1, 30, v1
	s_and_b64 s[24:25], vcc, s[0:1]
	v_cmp_ge_u32_e32 vcc, v174, v32
	v_cmp_lt_u32_e64 s[0:1], v174, v2
	v_lshlrev_b32_e32 v212, 2, v1
	v_max_i32_e32 v1, 0xffffffe0, v0
	s_and_b64 s[26:27], vcc, s[0:1]
	v_cmp_ge_u32_e32 vcc, v175, v32
	v_cmp_lt_u32_e64 s[0:1], v175, v2
	v_add_u32_e32 v1, 32, v1
	s_and_b64 s[28:29], vcc, s[0:1]
	v_cmp_ge_u32_e32 vcc, v176, v32
	v_cmp_lt_u32_e64 s[0:1], v176, v2
	v_min_u32_e32 v1, 30, v1
	s_and_b64 s[30:31], vcc, s[0:1]
	v_cmp_ge_u32_e32 vcc, v177, v32
	v_cmp_lt_u32_e64 s[0:1], v177, v2
	v_lshlrev_b32_e32 v213, 2, v1
	v_max_i32_e32 v1, 0xffffffe1, v0
	s_and_b64 s[34:35], vcc, s[0:1]
	v_cmp_ge_u32_e32 vcc, v132, v32
	v_cmp_lt_u32_e64 s[0:1], v170, v32
	v_add_u32_e32 v1, 31, v1
	s_and_b64 s[36:37], vcc, s[0:1]
	v_cmp_ge_u32_e32 vcc, v135, v32
	v_cmp_lt_u32_e64 s[0:1], v171, v32
	v_min_u32_e32 v1, 30, v1
	s_and_b64 s[38:39], vcc, s[0:1]
	v_cmp_ge_u32_e32 vcc, v134, v32
	v_cmp_lt_u32_e64 s[0:1], v172, v32
	v_lshlrev_b32_e32 v214, 2, v1
	v_max_i32_e32 v1, 0xffffffe6, v0
	s_and_b64 s[40:41], vcc, s[0:1]
	v_cmp_ge_u32_e32 vcc, v137, v32
	v_cmp_lt_u32_e64 s[0:1], v173, v32
	v_lshlrev_b32_e32 v215, 2, v1
	v_max_i32_e32 v1, 0xffffffe7, v0
	s_and_b64 s[42:43], vcc, s[0:1]
	v_cmp_ge_u32_e32 vcc, v136, v32
	v_cmp_lt_u32_e64 s[0:1], v174, v32
	v_lshlrev_b32_e32 v216, 2, v1
	v_max_i32_e32 v1, 0xffffffe8, v0
	s_and_b64 s[54:55], vcc, s[0:1]
	v_cmp_ge_u32_e32 vcc, v139, v32
	v_cmp_lt_u32_e64 s[0:1], v175, v32
	v_lshlrev_b32_e32 v217, 2, v1
	v_max_i32_e32 v1, 0xffffffe9, v0
	s_and_b64 s[56:57], vcc, s[0:1]
	v_cmp_ge_u32_e32 vcc, v138, v32
	v_cmp_lt_u32_e64 s[0:1], v176, v32
	v_lshlrev_b32_e32 v218, 2, v1
	v_max_i32_e32 v1, 0xffffffee, v0
	s_and_b64 s[58:59], vcc, s[0:1]
	v_cmp_ge_u32_e32 vcc, v141, v32
	v_cmp_lt_u32_e64 s[0:1], v177, v32
	v_lshlrev_b32_e32 v219, 2, v1
	v_max_i32_e32 v1, 0xffffffef, v0
	s_and_b64 s[60:61], vcc, s[0:1]
	v_lshlrev_b32_e32 v220, 2, v1
	v_max_i32_e32 v1, -16, v0
	v_max_i32_e32 v0, -15, v0
	s_add_i32 s0, s66, s67
	v_mov_b32_e32 v232, 0
	v_cmp_lt_u32_e64 s[8:9], v133, v32
	v_cmp_lt_u32_e64 s[44:45], v135, v32
	v_cmp_lt_u32_e64 s[46:47], v132, v32
	v_cmp_lt_u32_e64 s[48:49], v137, v32
	v_cmp_lt_u32_e64 s[50:51], v134, v32
	v_cmp_lt_u32_e64 s[52:53], v139, v32
	v_cmp_lt_u32_e64 s[62:63], v136, v32
	v_cmp_lt_u32_e64 s[64:65], v141, v32
	v_lshl_add_u64 v[162:163], s[74:75], 0, v[194:195]
	v_lshl_add_u64 v[162:163], v[162:163], 0, s[72:73]
	v_lshlrev_b32_e32 v221, 2, v1
	v_lshlrev_b32_e32 v231, 2, v0
	s_add_i32 s87, s0, 0x60
	v_mov_b32_e32 v140, 0xf149f2ca
	s_mov_b32 s93, -14
	v_mov_b32_e32 v16, 0
	v_mov_b32_e32 v17, v232
	v_mov_b32_e32 v18, v232
	v_mov_b32_e32 v19, v232
	v_mov_b32_e32 v20, v232
	v_mov_b32_e32 v21, v232
	v_mov_b32_e32 v22, v232
	v_mov_b32_e32 v23, v232
	v_mov_b32_e32 v24, v232
	v_mov_b32_e32 v25, v232
	v_mov_b32_e32 v26, v232
	v_mov_b32_e32 v27, v232
	v_mov_b32_e32 v28, v232
	v_mov_b32_e32 v29, v232
	v_mov_b32_e32 v30, v232
	v_mov_b32_e32 v31, v232
	v_mov_b32_e32 v0, 0
	v_mov_b32_e32 v1, v232
	v_mov_b32_e32 v2, v232
	v_mov_b32_e32 v3, v232
	v_mov_b32_e32 v4, v232
	v_mov_b32_e32 v5, v232
	v_mov_b32_e32 v6, v232
	v_mov_b32_e32 v7, v232
	v_mov_b32_e32 v8, v232
	v_mov_b32_e32 v9, v232
	v_mov_b32_e32 v10, v232
	v_mov_b32_e32 v11, v232
	v_mov_b32_e32 v12, v232
	v_mov_b32_e32 v13, v232
	v_mov_b32_e32 v14, v232
	v_mov_b32_e32 v15, v232
	s_mov_b32 s83, s88
	v_cmp_lt_u32_e64 s[66:67], v138, v32
	s_branch .LBB0_611
